# attention top-8 selection ranking rewritten: one compare + one add-with-carry per pair (ge below own index, gt above), SGPR carries pipelined
# speedup vs baseline: 1.0188x; 1.0060x over previous
; DI void attn_phase(const Params& p, const int layer, const int wid_s) {
;     ...
;         const float gl = (float)hb[(size_t)t * LDH + C_GL + (hh0 + hp) * 3 + br];
;         gate[hp][br] = 1.f / (1.f + __expf(-gl));
;     ...
; #pragma unroll
;         for (int dt = 0; dt < 4; ++dt)
; #pragma unroll
;           for (int j = 0; j < 4; ++j) fin[(hp * 16 + dt * 4 + j) * 64] = o[dt][j] * gate_c;
;       }
;       unsigned mk = (2u << cur) - 1u;
;       if (cur >= 8) {
;       float impv[8];
;       __syncthreads();
; #pragma unroll
;       for (int nt = 0; nt < 8; ++nt) {
;         const float mine = impx[(wave * 8 + nt) * 64], other = impx[((wave ^ 4) * 8 + nt) * 64];
;         const float im = hpair == 0 ? mine + other : other + mine;
;         const int jb = nt * 4 + fql;
;         const bool forced = (jb == 0) || (jb == cur) || (jb == cur - 1);
;         impv[nt] = jb <= cur ? im + (forced ? 1e6f : 0.f) : NEGF;
;         impb[jb] = impv[nt];
;       }
.LBB0_332:
	v_cvt_f32_f16_sdwa v0, v121 dst_sel:DWORD dst_unused:UNUSED_PAD src0_sel:WORD_1
	v_mul_f32_e32 v0, 0xbfb8aa3b, v0
	v_exp_f32_e32 v0, v0
	s_nop 0
	v_add_f32_e32 v0, 1.0, v0
	v_div_scale_f32 v2, s[4:5], v0, v0, 1.0
	v_rcp_f32_e32 v3, v2
	v_div_scale_f32 v5, vcc, 1.0, v0, 1.0
	s_lshl_b32 s4, 2, s54
	v_fma_f32 v6, -v2, v3, 1.0
	v_fmac_f32_e32 v3, v6, v3
	v_mul_f32_e32 v6, v5, v3
	v_fma_f32 v7, -v2, v6, v5
	v_fmac_f32_e32 v6, v7, v3
	v_fma_f32 v2, -v2, v6, v5
	v_div_fmas_f32 v2, v2, v3, v6
	v_div_fixup_f32 v0, v2, v0, 1.0
	v_mul_f32_e32 v2, v0, v36
	v_mul_f32_e32 v3, v0, v37
	v_mul_f32_e32 v5, v0, v38
	v_mul_f32_e32 v6, v0, v39
	v_mul_f32_e32 v7, v0, v28
	ds_write2st64_b32 v188, v2, v3 offset0:168 offset1:169
	ds_write2st64_b32 v188, v5, v6 offset0:170 offset1:171
	v_mul_f32_e32 v2, v0, v29
	ds_write2st64_b32 v188, v7, v2 offset0:172 offset1:173
	v_mul_f32_e32 v2, v0, v30
	v_mul_f32_e32 v3, v0, v31
	ds_write2st64_b32 v188, v2, v3 offset0:174 offset1:175
	v_mul_f32_e32 v2, v0, v32
	v_mul_f32_e32 v3, v0, v33
	ds_write2st64_b32 v188, v2, v3 offset0:176 offset1:177
	v_mul_f32_e32 v2, v0, v34
	v_mul_f32_e32 v3, v0, v35
	ds_write2st64_b32 v188, v2, v3 offset0:178 offset1:179
	v_mul_f32_e32 v2, v0, v24
	v_mul_f32_e32 v3, v0, v25
	s_add_i32 s4, s4, -1
	ds_write2st64_b32 v188, v2, v3 offset0:180 offset1:181
	v_mul_f32_e32 v2, v0, v26
	v_mul_f32_e32 v0, v0, v27
	s_and_b64 vcc, exec, s[0:1]
	v_mov_b32_e32 v5, s4
	ds_write2st64_b32 v188, v2, v0 offset0:182 offset1:183
	s_cbranch_vccnz .LBB0_334
	s_waitcnt lgkmcnt(0)
	s_barrier
	ds_read_b32 v0, v151 offset:22656
	ds_read_b32 v2, v182 offset:22656
	s_add_i32 s6, s54, -1
	v_cmp_eq_u32_e32 vcc, 0, v123
	v_cmp_eq_u32_e64 s[0:1], s54, v123
	s_or_b64 s[0:1], vcc, s[0:1]
	v_cmp_eq_u32_e32 vcc, s6, v123
	s_or_b64 vcc, s[0:1], vcc
	s_waitcnt lgkmcnt(0)
	v_add_f32_e32 v0, v0, v2
	v_cndmask_b32_e32 v2, 0, v159, vcc
	v_add_f32_e32 v0, v2, v0
	v_cmp_lt_i32_e64 s[0:1], s54, v123
	v_lshl_add_u32 v24, v123, 2, v147
	v_add_u32_e32 v32, 28, v123
	v_writelane_b32 v249, s0, 58
	v_cmp_lt_i32_e64 s[40:41], s54, v32
	v_cmp_lt_i32_e64 s[56:57], 0, v123
	v_cndmask_b32_e64 v39, v0, v4, s[0:1]
	ds_write_b32 v24, v39 offset:4224
	ds_read_b32 v0, v151 offset:22912
	ds_read_b32 v2, v182 offset:22912
	v_writelane_b32 v249, s1, 59
	v_cmp_lt_i32_e64 s[58:59], 2, v123
	v_cmp_lt_i32_e64 s[60:61], 3, v123
	v_cmp_lt_i32_e64 s[74:75], -4, v123
	s_waitcnt lgkmcnt(0)
	v_add_f32_e32 v2, v0, v2
	v_add_u32_e32 v0, 4, v123
	v_cmp_eq_u32_e32 vcc, 0, v0
	v_cmp_eq_u32_e64 s[4:5], s54, v0
	s_or_b64 s[0:1], vcc, s[4:5]
	v_cmp_eq_u32_e32 vcc, s6, v0
	s_or_b64 vcc, s[0:1], vcc
	v_cmp_lt_i32_e64 s[0:1], s54, v0
	v_cndmask_b32_e32 v3, 0, v159, vcc
	v_add_f32_e32 v2, v3, v2
	v_writelane_b32 v249, s0, 60
	v_cmp_lt_i32_e64 s[72:73], -3, v123
	v_cmp_lt_i32_e64 s[62:63], -1, v123
	v_cndmask_b32_e64 v40, v2, v4, s[0:1]
	ds_write_b32 v24, v40 offset:4240
	ds_read_b32 v2, v151 offset:23168
	ds_read_b32 v3, v182 offset:23168
	v_writelane_b32 v249, s1, 61
	v_readlane_b32 s84, v252, 44
	v_readlane_b32 s85, v252, 45
	v_readlane_b32 s88, v252, 48
	s_waitcnt lgkmcnt(0)
	v_add_f32_e32 v3, v2, v3
	v_add_u32_e32 v2, 8, v123
	v_cmp_eq_u32_e32 vcc, 0, v2
	v_cmp_eq_u32_e64 s[4:5], s54, v2
	s_or_b64 s[0:1], vcc, s[4:5]
	v_cmp_eq_u32_e32 vcc, s6, v2
	s_or_b64 vcc, s[0:1], vcc
	v_cmp_lt_i32_e64 s[0:1], s54, v2
	v_cndmask_b32_e32 v5, 0, v159, vcc
	v_add_f32_e32 v3, v5, v3
	v_writelane_b32 v249, s0, 62
	v_readlane_b32 s89, v252, 49
	v_cmp_lt_i32_e64 s[88:89], -8, v123
	v_cndmask_b32_e64 v38, v3, v4, s[0:1]
	ds_write_b32 v24, v38 offset:4256
	ds_read_b32 v3, v151 offset:23424
	ds_read_b32 v5, v182 offset:23424
	v_writelane_b32 v249, s1, 63
	v_cmp_lt_i32_e64 s[84:85], -7, v123
	v_readlane_b32 s90, v252, 50
	v_readlane_b32 s91, v252, 51
	s_waitcnt lgkmcnt(0)
	v_add_f32_e32 v5, v3, v5
	v_add_u32_e32 v3, 12, v123
	v_cmp_eq_u32_e32 vcc, 0, v3
	v_cmp_eq_u32_e64 s[4:5], s54, v3
	s_or_b64 s[0:1], vcc, s[4:5]
	v_cmp_eq_u32_e32 vcc, s6, v3
	s_or_b64 vcc, s[0:1], vcc
	v_cmp_lt_i32_e64 s[0:1], s54, v3
	v_cndmask_b32_e32 v6, 0, v159, vcc
	v_add_f32_e32 v5, v6, v5
	v_writelane_b32 v248, s0, 0
	v_cmp_lt_i32_e64 s[90:91], -6, v123
	v_readlane_b32 s92, v252, 52
	v_cndmask_b32_e64 v37, v5, v4, s[0:1]
	ds_write_b32 v24, v37 offset:4272
	ds_read_b32 v5, v151 offset:23680
	ds_read_b32 v6, v182 offset:23680
	v_writelane_b32 v248, s1, 1
	v_writelane_b32 v248, s39, 2
	s_mov_b32 s39, s77
	v_cmp_lt_i32_e64 s[76:77], -2, v123
	s_waitcnt lgkmcnt(0)
	v_add_f32_e32 v6, v5, v6
	v_add_u32_e32 v5, 16, v123
	v_cmp_eq_u32_e32 vcc, 0, v5
	v_cmp_eq_u32_e64 s[4:5], s54, v5
	s_or_b64 s[0:1], vcc, s[4:5]
	v_cmp_eq_u32_e32 vcc, s6, v5
	s_or_b64 vcc, s[0:1], vcc
	v_cmp_lt_i32_e64 s[46:47], s54, v5
	v_cndmask_b32_e32 v7, 0, v159, vcc
	v_add_f32_e32 v6, v7, v6
	v_cndmask_b32_e64 v36, v6, v4, s[46:47]
	ds_write_b32 v24, v36 offset:4288
	ds_read_b32 v6, v151 offset:23936
	ds_read_b32 v7, v182 offset:23936
	v_readlane_b32 s93, v252, 53
	v_cmp_lt_i32_e64 s[92:93], -5, v123
	v_cmp_lt_i32_e64 s[10:11], -12, v123
	v_cmp_lt_i32_e64 s[20:21], -10, v123
	s_waitcnt lgkmcnt(0)
	v_add_f32_e32 v7, v6, v7
	v_add_u32_e32 v6, 20, v123
	v_cmp_eq_u32_e32 vcc, 0, v6
	v_cmp_eq_u32_e64 s[4:5], s54, v6
	s_or_b64 s[0:1], vcc, s[4:5]
	v_cmp_eq_u32_e32 vcc, s6, v6
	s_or_b64 vcc, s[0:1], vcc
	v_cmp_lt_i32_e64 s[44:45], s54, v6
	v_cndmask_b32_e32 v25, 0, v159, vcc
	v_add_f32_e32 v7, v25, v7
	v_cndmask_b32_e64 v35, v7, v4, s[44:45]
	ds_write_b32 v24, v35 offset:4304
	ds_read_b32 v7, v151 offset:24192
	ds_read_b32 v25, v182 offset:24192
	v_readlane_b32 s94, v252, 54
	v_readlane_b32 s95, v252, 55
	v_cmp_lt_i32_e64 s[94:95], -9, v123
	v_cmp_lt_i32_e64 s[14:15], -16, v123
	s_waitcnt lgkmcnt(0)
	v_add_f32_e32 v25, v7, v25
	v_add_u32_e32 v7, 24, v123
	v_cmp_eq_u32_e32 vcc, 0, v7
	v_cmp_eq_u32_e64 s[4:5], s54, v7
	s_or_b64 s[0:1], vcc, s[4:5]
	v_cmp_eq_u32_e32 vcc, s6, v7
	s_or_b64 vcc, s[0:1], vcc
	v_cmp_lt_i32_e64 s[42:43], s54, v7
	v_cndmask_b32_e32 v26, 0, v159, vcc
	v_add_f32_e32 v25, v26, v25
	v_cndmask_b32_e64 v34, v25, v4, s[42:43]
	ds_write_b32 v24, v34 offset:4320
	ds_read_b32 v25, v151 offset:24448
	ds_read_b32 v26, v182 offset:24448
	v_cmp_eq_u32_e32 vcc, 0, v32
	v_cmp_eq_u32_e64 s[4:5], s54, v32
	s_or_b64 s[0:1], vcc, s[4:5]
	v_cmp_eq_u32_e32 vcc, s6, v32
	s_or_b64 vcc, s[0:1], vcc
	s_waitcnt lgkmcnt(0)
	v_add_f32_e32 v25, v25, v26
	v_cndmask_b32_e32 v26, 0, v159, vcc
	v_add_f32_e32 v25, v26, v25
	v_cndmask_b32_e64 v33, v25, v4, s[40:41]
	ds_write_b32 v24, v33 offset:4336
	s_waitcnt lgkmcnt(0)
	s_barrier
; #define LAS __attribute__((address_space(3)))
; DI void attn_phase(const Params& p, const int layer, const int wid_s) {
;     ...
;       int cnt[8];
; #pragma unroll
;       for (int nt = 0; nt < 8; ++nt) cnt[nt] = 0;
; #pragma unroll
;       for (int i = 0; i < 8; ++i) {
;         const f32x4 r4 = *(const LAS f32x4*)(impb + 4 * i);
;         const float rv[4] = {r4[0], r4[1], r4[2], r4[3]};
; #pragma unroll
;         for (int nt = 0; nt < 8; ++nt) {
;           const float a = impv[nt]; const int ja = nt * 4 + fql;
; #pragma unroll
;           for (int c = 0; c < 4; ++c) cnt[nt] += (int)(rv[c] > a) | ((int)(rv[c] == a) & (int)((4 * i + c) < ja));
;         }
;       }
	ds_read_b128 v[198:201], v147 offset:4224
	ds_read_b128 v[202:205], v147 offset:4240
	ds_read_b128 v[206:209], v147 offset:4256
	ds_read_b128 v[210:213], v147 offset:4272
	ds_read_b128 v[214:217], v147 offset:4288
	ds_read_b128 v[218:221], v147 offset:4304
	ds_read_b128 v[222:225], v147 offset:4320
	ds_read_b128 v[226:229], v147 offset:4336
	v_cmp_lt_i32_e64 s[6:7], 0, v123
	v_cmp_lt_i32_e64 s[8:9], 1, v123
	v_cmp_lt_i32_e64 s[10:11], 2, v123
	v_mov_b32_e32 v230, 0
	v_mov_b32_e32 v231, 0
	v_mov_b32_e32 v232, 0
	v_mov_b32_e32 v233, 0
	v_mov_b32_e32 v234, 0
	v_mov_b32_e32 v235, 0
	v_mov_b32_e32 v236, 0
	v_mov_b32_e32 v237, 0
	s_waitcnt lgkmcnt(0)
	v_cmp_gt_f32_e64 s[12:13], v198, v39
	v_cmp_ge_f32_e64 s[20:21], v198, v39
	s_and_b64 s[20:21], s[20:21], s[6:7]
	s_or_b64 s[12:13], s[12:13], s[20:21]
	v_cmp_gt_f32_e64 s[14:15], v199, v39
	v_cmp_ge_f32_e64 s[20:21], v199, v39
	s_and_b64 s[20:21], s[20:21], s[8:9]
	s_or_b64 s[14:15], s[14:15], s[20:21]
	v_cmp_gt_f32_e64 s[16:17], v200, v39
	v_cmp_ge_f32_e64 s[20:21], v200, v39
	s_and_b64 s[20:21], s[20:21], s[10:11]
	s_or_b64 s[16:17], s[16:17], s[20:21]
	v_addc_co_u32_e64 v230, s[18:19], 0, v230, s[12:13]
	v_cmp_gt_f32_e64 s[12:13], v201, v39
	v_addc_co_u32_e64 v230, s[18:19], 0, v230, s[14:15]
	v_cmp_gt_f32_e64 s[14:15], v202, v39
	v_addc_co_u32_e64 v230, s[18:19], 0, v230, s[16:17]
	v_cmp_gt_f32_e64 s[16:17], v203, v39
	v_addc_co_u32_e64 v230, s[18:19], 0, v230, s[12:13]
	v_cmp_gt_f32_e64 s[12:13], v204, v39
	v_addc_co_u32_e64 v230, s[18:19], 0, v230, s[14:15]
	v_cmp_gt_f32_e64 s[14:15], v205, v39
	v_addc_co_u32_e64 v230, s[18:19], 0, v230, s[16:17]
	v_cmp_gt_f32_e64 s[16:17], v206, v39
	v_addc_co_u32_e64 v230, s[18:19], 0, v230, s[12:13]
	v_cmp_gt_f32_e64 s[12:13], v207, v39
	v_addc_co_u32_e64 v230, s[18:19], 0, v230, s[14:15]
	v_cmp_gt_f32_e64 s[14:15], v208, v39
	v_addc_co_u32_e64 v230, s[18:19], 0, v230, s[16:17]
	v_cmp_gt_f32_e64 s[16:17], v209, v39
	v_addc_co_u32_e64 v230, s[18:19], 0, v230, s[12:13]
	v_cmp_gt_f32_e64 s[12:13], v210, v39
	v_addc_co_u32_e64 v230, s[18:19], 0, v230, s[14:15]
	v_cmp_gt_f32_e64 s[14:15], v211, v39
	v_addc_co_u32_e64 v230, s[18:19], 0, v230, s[16:17]
	v_cmp_gt_f32_e64 s[16:17], v212, v39
	v_addc_co_u32_e64 v230, s[18:19], 0, v230, s[12:13]
	v_cmp_gt_f32_e64 s[12:13], v213, v39
	v_addc_co_u32_e64 v230, s[18:19], 0, v230, s[14:15]
	v_cmp_gt_f32_e64 s[14:15], v214, v39
	v_addc_co_u32_e64 v230, s[18:19], 0, v230, s[16:17]
	v_cmp_gt_f32_e64 s[16:17], v215, v39
	v_addc_co_u32_e64 v230, s[18:19], 0, v230, s[12:13]
	v_cmp_gt_f32_e64 s[12:13], v216, v39
	v_addc_co_u32_e64 v230, s[18:19], 0, v230, s[14:15]
	v_cmp_gt_f32_e64 s[14:15], v217, v39
	v_addc_co_u32_e64 v230, s[18:19], 0, v230, s[16:17]
	v_cmp_gt_f32_e64 s[16:17], v218, v39
	v_addc_co_u32_e64 v230, s[18:19], 0, v230, s[12:13]
	v_cmp_gt_f32_e64 s[12:13], v219, v39
	v_addc_co_u32_e64 v230, s[18:19], 0, v230, s[14:15]
	v_cmp_gt_f32_e64 s[14:15], v220, v39
	v_addc_co_u32_e64 v230, s[18:19], 0, v230, s[16:17]
	v_cmp_gt_f32_e64 s[16:17], v221, v39
	v_addc_co_u32_e64 v230, s[18:19], 0, v230, s[12:13]
	v_cmp_gt_f32_e64 s[12:13], v222, v39
	v_addc_co_u32_e64 v230, s[18:19], 0, v230, s[14:15]
	v_cmp_gt_f32_e64 s[14:15], v223, v39
	v_addc_co_u32_e64 v230, s[18:19], 0, v230, s[16:17]
	v_cmp_gt_f32_e64 s[16:17], v224, v39
	v_addc_co_u32_e64 v230, s[18:19], 0, v230, s[12:13]
	v_cmp_gt_f32_e64 s[12:13], v225, v39
	v_addc_co_u32_e64 v230, s[18:19], 0, v230, s[14:15]
	v_cmp_gt_f32_e64 s[14:15], v226, v39
	v_addc_co_u32_e64 v230, s[18:19], 0, v230, s[16:17]
	v_cmp_gt_f32_e64 s[16:17], v227, v39
	v_addc_co_u32_e64 v230, s[18:19], 0, v230, s[12:13]
	v_cmp_gt_f32_e64 s[12:13], v228, v39
	v_addc_co_u32_e64 v230, s[18:19], 0, v230, s[14:15]
	v_cmp_gt_f32_e64 s[14:15], v229, v39
	v_addc_co_u32_e64 v230, s[18:19], 0, v230, s[16:17]
	v_cmp_ge_f32_e64 s[16:17], v198, v40
	v_addc_co_u32_e64 v230, s[18:19], 0, v230, s[12:13]
	v_cmp_ge_f32_e64 s[12:13], v199, v40
	v_addc_co_u32_e64 v230, s[18:19], 0, v230, s[14:15]
	v_cmp_ge_f32_e64 s[14:15], v200, v40
	v_addc_co_u32_e64 v231, s[18:19], 0, v231, s[16:17]
	v_cmp_ge_f32_e64 s[16:17], v201, v40
	v_addc_co_u32_e64 v231, s[18:19], 0, v231, s[12:13]
	v_cmp_gt_f32_e64 s[12:13], v202, v40
	v_cmp_ge_f32_e64 s[20:21], v202, v40
	s_and_b64 s[20:21], s[20:21], s[6:7]
	s_or_b64 s[12:13], s[12:13], s[20:21]
	v_addc_co_u32_e64 v231, s[18:19], 0, v231, s[14:15]
	v_cmp_gt_f32_e64 s[14:15], v203, v40
	v_cmp_ge_f32_e64 s[20:21], v203, v40
	s_and_b64 s[20:21], s[20:21], s[8:9]
	s_or_b64 s[14:15], s[14:15], s[20:21]
	v_addc_co_u32_e64 v231, s[18:19], 0, v231, s[16:17]
	v_cmp_gt_f32_e64 s[16:17], v204, v40
	v_cmp_ge_f32_e64 s[20:21], v204, v40
	s_and_b64 s[20:21], s[20:21], s[10:11]
	s_or_b64 s[16:17], s[16:17], s[20:21]
	v_addc_co_u32_e64 v231, s[18:19], 0, v231, s[12:13]
	v_cmp_gt_f32_e64 s[12:13], v205, v40
	v_addc_co_u32_e64 v231, s[18:19], 0, v231, s[14:15]
	v_cmp_gt_f32_e64 s[14:15], v206, v40
	v_addc_co_u32_e64 v231, s[18:19], 0, v231, s[16:17]
	v_cmp_gt_f32_e64 s[16:17], v207, v40
	v_addc_co_u32_e64 v231, s[18:19], 0, v231, s[12:13]
	v_cmp_gt_f32_e64 s[12:13], v208, v40
	v_addc_co_u32_e64 v231, s[18:19], 0, v231, s[14:15]
	v_cmp_gt_f32_e64 s[14:15], v209, v40
	v_addc_co_u32_e64 v231, s[18:19], 0, v231, s[16:17]
	v_cmp_gt_f32_e64 s[16:17], v210, v40
	v_addc_co_u32_e64 v231, s[18:19], 0, v231, s[12:13]
	v_cmp_gt_f32_e64 s[12:13], v211, v40
	v_addc_co_u32_e64 v231, s[18:19], 0, v231, s[14:15]
	v_cmp_gt_f32_e64 s[14:15], v212, v40
	v_addc_co_u32_e64 v231, s[18:19], 0, v231, s[16:17]
	v_cmp_gt_f32_e64 s[16:17], v213, v40
	v_addc_co_u32_e64 v231, s[18:19], 0, v231, s[12:13]
	v_cmp_gt_f32_e64 s[12:13], v214, v40
; #define LAS __attribute__((address_space(3)))
; DI void attn_phase(const Params& p, const int layer, const int wid_s) {
;     ...
;       for (int i = 0; i < 8; ++i) {
;         const f32x4 r4 = *(const LAS f32x4*)(impb + 4 * i);
;         const float rv[4] = {r4[0], r4[1], r4[2], r4[3]};
; #pragma unroll
;         for (int nt = 0; nt < 8; ++nt) {
;           const float a = impv[nt]; const int ja = nt * 4 + fql;
; #pragma unroll
;           for (int c = 0; c < 4; ++c) cnt[nt] += (int)(rv[c] > a) | ((int)(rv[c] == a) & (int)((4 * i + c) < ja));
;         }
	v_addc_co_u32_e64 v231, s[18:19], 0, v231, s[14:15]
	v_cmp_gt_f32_e64 s[14:15], v215, v40
	v_addc_co_u32_e64 v231, s[18:19], 0, v231, s[16:17]
	v_cmp_gt_f32_e64 s[16:17], v216, v40
	v_addc_co_u32_e64 v231, s[18:19], 0, v231, s[12:13]
	v_cmp_gt_f32_e64 s[12:13], v217, v40
	v_addc_co_u32_e64 v231, s[18:19], 0, v231, s[14:15]
	v_cmp_gt_f32_e64 s[14:15], v218, v40
	v_addc_co_u32_e64 v231, s[18:19], 0, v231, s[16:17]
	v_cmp_gt_f32_e64 s[16:17], v219, v40
	v_addc_co_u32_e64 v231, s[18:19], 0, v231, s[12:13]
	v_cmp_gt_f32_e64 s[12:13], v220, v40
	v_addc_co_u32_e64 v231, s[18:19], 0, v231, s[14:15]
	v_cmp_gt_f32_e64 s[14:15], v221, v40
	v_addc_co_u32_e64 v231, s[18:19], 0, v231, s[16:17]
	v_cmp_gt_f32_e64 s[16:17], v222, v40
	v_addc_co_u32_e64 v231, s[18:19], 0, v231, s[12:13]
	v_cmp_gt_f32_e64 s[12:13], v223, v40
	v_addc_co_u32_e64 v231, s[18:19], 0, v231, s[14:15]
	v_cmp_gt_f32_e64 s[14:15], v224, v40
	v_addc_co_u32_e64 v231, s[18:19], 0, v231, s[16:17]
	v_cmp_gt_f32_e64 s[16:17], v225, v40
	v_addc_co_u32_e64 v231, s[18:19], 0, v231, s[12:13]
	v_cmp_gt_f32_e64 s[12:13], v226, v40
	v_addc_co_u32_e64 v231, s[18:19], 0, v231, s[14:15]
	v_cmp_gt_f32_e64 s[14:15], v227, v40
	v_addc_co_u32_e64 v231, s[18:19], 0, v231, s[16:17]
	v_cmp_gt_f32_e64 s[16:17], v228, v40
	v_addc_co_u32_e64 v231, s[18:19], 0, v231, s[12:13]
	v_cmp_gt_f32_e64 s[12:13], v229, v40
	v_addc_co_u32_e64 v231, s[18:19], 0, v231, s[14:15]
	v_cmp_ge_f32_e64 s[14:15], v198, v38
	v_addc_co_u32_e64 v231, s[18:19], 0, v231, s[16:17]
	v_cmp_ge_f32_e64 s[16:17], v199, v38
	v_addc_co_u32_e64 v231, s[18:19], 0, v231, s[12:13]
	v_cmp_ge_f32_e64 s[12:13], v200, v38
	v_addc_co_u32_e64 v232, s[18:19], 0, v232, s[14:15]
	v_cmp_ge_f32_e64 s[14:15], v201, v38
	v_addc_co_u32_e64 v232, s[18:19], 0, v232, s[16:17]
	v_cmp_ge_f32_e64 s[16:17], v202, v38
	v_addc_co_u32_e64 v232, s[18:19], 0, v232, s[12:13]
	v_cmp_ge_f32_e64 s[12:13], v203, v38
	v_addc_co_u32_e64 v232, s[18:19], 0, v232, s[14:15]
	v_cmp_ge_f32_e64 s[14:15], v204, v38
	v_addc_co_u32_e64 v232, s[18:19], 0, v232, s[16:17]
	v_cmp_ge_f32_e64 s[16:17], v205, v38
	v_addc_co_u32_e64 v232, s[18:19], 0, v232, s[12:13]
	v_cmp_gt_f32_e64 s[12:13], v206, v38
	v_cmp_ge_f32_e64 s[20:21], v206, v38
	s_and_b64 s[20:21], s[20:21], s[6:7]
	s_or_b64 s[12:13], s[12:13], s[20:21]
	v_addc_co_u32_e64 v232, s[18:19], 0, v232, s[14:15]
	v_cmp_gt_f32_e64 s[14:15], v207, v38
	v_cmp_ge_f32_e64 s[20:21], v207, v38
	s_and_b64 s[20:21], s[20:21], s[8:9]
	s_or_b64 s[14:15], s[14:15], s[20:21]
	v_addc_co_u32_e64 v232, s[18:19], 0, v232, s[16:17]
	v_cmp_gt_f32_e64 s[16:17], v208, v38
	v_cmp_ge_f32_e64 s[20:21], v208, v38
	s_and_b64 s[20:21], s[20:21], s[10:11]
	s_or_b64 s[16:17], s[16:17], s[20:21]
	v_addc_co_u32_e64 v232, s[18:19], 0, v232, s[12:13]
	v_cmp_gt_f32_e64 s[12:13], v209, v38
	v_addc_co_u32_e64 v232, s[18:19], 0, v232, s[14:15]
	v_cmp_gt_f32_e64 s[14:15], v210, v38
	v_addc_co_u32_e64 v232, s[18:19], 0, v232, s[16:17]
	v_cmp_gt_f32_e64 s[16:17], v211, v38
	v_addc_co_u32_e64 v232, s[18:19], 0, v232, s[12:13]
	v_cmp_gt_f32_e64 s[12:13], v212, v38
	v_addc_co_u32_e64 v232, s[18:19], 0, v232, s[14:15]
	v_cmp_gt_f32_e64 s[14:15], v213, v38
	v_addc_co_u32_e64 v232, s[18:19], 0, v232, s[16:17]
	v_cmp_gt_f32_e64 s[16:17], v214, v38
	v_addc_co_u32_e64 v232, s[18:19], 0, v232, s[12:13]
	v_cmp_gt_f32_e64 s[12:13], v215, v38
	v_addc_co_u32_e64 v232, s[18:19], 0, v232, s[14:15]
	v_cmp_gt_f32_e64 s[14:15], v216, v38
	v_addc_co_u32_e64 v232, s[18:19], 0, v232, s[16:17]
	v_cmp_gt_f32_e64 s[16:17], v217, v38
	v_addc_co_u32_e64 v232, s[18:19], 0, v232, s[12:13]
	v_cmp_gt_f32_e64 s[12:13], v218, v38
	v_addc_co_u32_e64 v232, s[18:19], 0, v232, s[14:15]
	v_cmp_gt_f32_e64 s[14:15], v219, v38
	v_addc_co_u32_e64 v232, s[18:19], 0, v232, s[16:17]
	v_cmp_gt_f32_e64 s[16:17], v220, v38
	v_addc_co_u32_e64 v232, s[18:19], 0, v232, s[12:13]
	v_cmp_gt_f32_e64 s[12:13], v221, v38
	v_addc_co_u32_e64 v232, s[18:19], 0, v232, s[14:15]
	v_cmp_gt_f32_e64 s[14:15], v222, v38
	v_addc_co_u32_e64 v232, s[18:19], 0, v232, s[16:17]
	v_cmp_gt_f32_e64 s[16:17], v223, v38
	v_addc_co_u32_e64 v232, s[18:19], 0, v232, s[12:13]
	v_cmp_gt_f32_e64 s[12:13], v224, v38
	v_addc_co_u32_e64 v232, s[18:19], 0, v232, s[14:15]
	v_cmp_gt_f32_e64 s[14:15], v225, v38
	v_addc_co_u32_e64 v232, s[18:19], 0, v232, s[16:17]
	v_cmp_gt_f32_e64 s[16:17], v226, v38
	v_addc_co_u32_e64 v232, s[18:19], 0, v232, s[12:13]
	v_cmp_gt_f32_e64 s[12:13], v227, v38
	v_addc_co_u32_e64 v232, s[18:19], 0, v232, s[14:15]
	v_cmp_gt_f32_e64 s[14:15], v228, v38
	v_addc_co_u32_e64 v232, s[18:19], 0, v232, s[16:17]
	v_cmp_gt_f32_e64 s[16:17], v229, v38
	v_addc_co_u32_e64 v232, s[18:19], 0, v232, s[12:13]
	v_cmp_ge_f32_e64 s[12:13], v198, v37
	v_addc_co_u32_e64 v232, s[18:19], 0, v232, s[14:15]
	v_cmp_ge_f32_e64 s[14:15], v199, v37
	v_addc_co_u32_e64 v232, s[18:19], 0, v232, s[16:17]
	v_cmp_ge_f32_e64 s[16:17], v200, v37
	v_addc_co_u32_e64 v233, s[18:19], 0, v233, s[12:13]
	v_cmp_ge_f32_e64 s[12:13], v201, v37
	v_addc_co_u32_e64 v233, s[18:19], 0, v233, s[14:15]
	v_cmp_ge_f32_e64 s[14:15], v202, v37
	v_addc_co_u32_e64 v233, s[18:19], 0, v233, s[16:17]
	v_cmp_ge_f32_e64 s[16:17], v203, v37
	v_addc_co_u32_e64 v233, s[18:19], 0, v233, s[12:13]
	v_cmp_ge_f32_e64 s[12:13], v204, v37
	v_addc_co_u32_e64 v233, s[18:19], 0, v233, s[14:15]
	v_cmp_ge_f32_e64 s[14:15], v205, v37
	v_addc_co_u32_e64 v233, s[18:19], 0, v233, s[16:17]
	v_cmp_ge_f32_e64 s[16:17], v206, v37
	v_addc_co_u32_e64 v233, s[18:19], 0, v233, s[12:13]
	v_cmp_ge_f32_e64 s[12:13], v207, v37
	v_addc_co_u32_e64 v233, s[18:19], 0, v233, s[14:15]
	v_cmp_ge_f32_e64 s[14:15], v208, v37
; #define LAS __attribute__((address_space(3)))
; DI void attn_phase(const Params& p, const int layer, const int wid_s) {
;     ...
;       for (int i = 0; i < 8; ++i) {
;         const f32x4 r4 = *(const LAS f32x4*)(impb + 4 * i);
;         const float rv[4] = {r4[0], r4[1], r4[2], r4[3]};
; #pragma unroll
;         for (int nt = 0; nt < 8; ++nt) {
;           const float a = impv[nt]; const int ja = nt * 4 + fql;
; #pragma unroll
;           for (int c = 0; c < 4; ++c) cnt[nt] += (int)(rv[c] > a) | ((int)(rv[c] == a) & (int)((4 * i + c) < ja));
;         }
	v_addc_co_u32_e64 v233, s[18:19], 0, v233, s[16:17]
	v_cmp_ge_f32_e64 s[16:17], v209, v37
	v_addc_co_u32_e64 v233, s[18:19], 0, v233, s[12:13]
	v_cmp_gt_f32_e64 s[12:13], v210, v37
	v_cmp_ge_f32_e64 s[20:21], v210, v37
	s_and_b64 s[20:21], s[20:21], s[6:7]
	s_or_b64 s[12:13], s[12:13], s[20:21]
	v_addc_co_u32_e64 v233, s[18:19], 0, v233, s[14:15]
	v_cmp_gt_f32_e64 s[14:15], v211, v37
	v_cmp_ge_f32_e64 s[20:21], v211, v37
	s_and_b64 s[20:21], s[20:21], s[8:9]
	s_or_b64 s[14:15], s[14:15], s[20:21]
	v_addc_co_u32_e64 v233, s[18:19], 0, v233, s[16:17]
	v_cmp_gt_f32_e64 s[16:17], v212, v37
	v_cmp_ge_f32_e64 s[20:21], v212, v37
	s_and_b64 s[20:21], s[20:21], s[10:11]
	s_or_b64 s[16:17], s[16:17], s[20:21]
	v_addc_co_u32_e64 v233, s[18:19], 0, v233, s[12:13]
	v_cmp_gt_f32_e64 s[12:13], v213, v37
	v_addc_co_u32_e64 v233, s[18:19], 0, v233, s[14:15]
	v_cmp_gt_f32_e64 s[14:15], v214, v37
	v_addc_co_u32_e64 v233, s[18:19], 0, v233, s[16:17]
	v_cmp_gt_f32_e64 s[16:17], v215, v37
	v_addc_co_u32_e64 v233, s[18:19], 0, v233, s[12:13]
	v_cmp_gt_f32_e64 s[12:13], v216, v37
	v_addc_co_u32_e64 v233, s[18:19], 0, v233, s[14:15]
	v_cmp_gt_f32_e64 s[14:15], v217, v37
	v_addc_co_u32_e64 v233, s[18:19], 0, v233, s[16:17]
	v_cmp_gt_f32_e64 s[16:17], v218, v37
	v_addc_co_u32_e64 v233, s[18:19], 0, v233, s[12:13]
	v_cmp_gt_f32_e64 s[12:13], v219, v37
	v_addc_co_u32_e64 v233, s[18:19], 0, v233, s[14:15]
	v_cmp_gt_f32_e64 s[14:15], v220, v37
	v_addc_co_u32_e64 v233, s[18:19], 0, v233, s[16:17]
	v_cmp_gt_f32_e64 s[16:17], v221, v37
	v_addc_co_u32_e64 v233, s[18:19], 0, v233, s[12:13]
	v_cmp_gt_f32_e64 s[12:13], v222, v37
	v_addc_co_u32_e64 v233, s[18:19], 0, v233, s[14:15]
	v_cmp_gt_f32_e64 s[14:15], v223, v37
	v_addc_co_u32_e64 v233, s[18:19], 0, v233, s[16:17]
	v_cmp_gt_f32_e64 s[16:17], v224, v37
	v_addc_co_u32_e64 v233, s[18:19], 0, v233, s[12:13]
	v_cmp_gt_f32_e64 s[12:13], v225, v37
	v_addc_co_u32_e64 v233, s[18:19], 0, v233, s[14:15]
	v_cmp_gt_f32_e64 s[14:15], v226, v37
	v_addc_co_u32_e64 v233, s[18:19], 0, v233, s[16:17]
	v_cmp_gt_f32_e64 s[16:17], v227, v37
	v_addc_co_u32_e64 v233, s[18:19], 0, v233, s[12:13]
	v_cmp_gt_f32_e64 s[12:13], v228, v37
	v_addc_co_u32_e64 v233, s[18:19], 0, v233, s[14:15]
	v_cmp_gt_f32_e64 s[14:15], v229, v37
	v_addc_co_u32_e64 v233, s[18:19], 0, v233, s[16:17]
	v_cmp_ge_f32_e64 s[16:17], v198, v36
	v_addc_co_u32_e64 v233, s[18:19], 0, v233, s[12:13]
	v_cmp_ge_f32_e64 s[12:13], v199, v36
	v_addc_co_u32_e64 v233, s[18:19], 0, v233, s[14:15]
	v_cmp_ge_f32_e64 s[14:15], v200, v36
	v_addc_co_u32_e64 v234, s[18:19], 0, v234, s[16:17]
	v_cmp_ge_f32_e64 s[16:17], v201, v36
	v_addc_co_u32_e64 v234, s[18:19], 0, v234, s[12:13]
	v_cmp_ge_f32_e64 s[12:13], v202, v36
	v_addc_co_u32_e64 v234, s[18:19], 0, v234, s[14:15]
	v_cmp_ge_f32_e64 s[14:15], v203, v36
	v_addc_co_u32_e64 v234, s[18:19], 0, v234, s[16:17]
	v_cmp_ge_f32_e64 s[16:17], v204, v36
	v_addc_co_u32_e64 v234, s[18:19], 0, v234, s[12:13]
	v_cmp_ge_f32_e64 s[12:13], v205, v36
	v_addc_co_u32_e64 v234, s[18:19], 0, v234, s[14:15]
	v_cmp_ge_f32_e64 s[14:15], v206, v36
	v_addc_co_u32_e64 v234, s[18:19], 0, v234, s[16:17]
	v_cmp_ge_f32_e64 s[16:17], v207, v36
	v_addc_co_u32_e64 v234, s[18:19], 0, v234, s[12:13]
	v_cmp_ge_f32_e64 s[12:13], v208, v36
	v_addc_co_u32_e64 v234, s[18:19], 0, v234, s[14:15]
	v_cmp_ge_f32_e64 s[14:15], v209, v36
	v_addc_co_u32_e64 v234, s[18:19], 0, v234, s[16:17]
	v_cmp_ge_f32_e64 s[16:17], v210, v36
	v_addc_co_u32_e64 v234, s[18:19], 0, v234, s[12:13]
	v_cmp_ge_f32_e64 s[12:13], v211, v36
	v_addc_co_u32_e64 v234, s[18:19], 0, v234, s[14:15]
	v_cmp_ge_f32_e64 s[14:15], v212, v36
	v_addc_co_u32_e64 v234, s[18:19], 0, v234, s[16:17]
	v_cmp_ge_f32_e64 s[16:17], v213, v36
	v_addc_co_u32_e64 v234, s[18:19], 0, v234, s[12:13]
	v_cmp_gt_f32_e64 s[12:13], v214, v36
	v_cmp_ge_f32_e64 s[20:21], v214, v36
	s_and_b64 s[20:21], s[20:21], s[6:7]
	s_or_b64 s[12:13], s[12:13], s[20:21]
	v_addc_co_u32_e64 v234, s[18:19], 0, v234, s[14:15]
	v_cmp_gt_f32_e64 s[14:15], v215, v36
	v_cmp_ge_f32_e64 s[20:21], v215, v36
	s_and_b64 s[20:21], s[20:21], s[8:9]
	s_or_b64 s[14:15], s[14:15], s[20:21]
	v_addc_co_u32_e64 v234, s[18:19], 0, v234, s[16:17]
	v_cmp_gt_f32_e64 s[16:17], v216, v36
	v_cmp_ge_f32_e64 s[20:21], v216, v36
	s_and_b64 s[20:21], s[20:21], s[10:11]
	s_or_b64 s[16:17], s[16:17], s[20:21]
	v_addc_co_u32_e64 v234, s[18:19], 0, v234, s[12:13]
	v_cmp_gt_f32_e64 s[12:13], v217, v36
	v_addc_co_u32_e64 v234, s[18:19], 0, v234, s[14:15]
	v_cmp_gt_f32_e64 s[14:15], v218, v36
	v_addc_co_u32_e64 v234, s[18:19], 0, v234, s[16:17]
	v_cmp_gt_f32_e64 s[16:17], v219, v36
	v_addc_co_u32_e64 v234, s[18:19], 0, v234, s[12:13]
	v_cmp_gt_f32_e64 s[12:13], v220, v36
	v_addc_co_u32_e64 v234, s[18:19], 0, v234, s[14:15]
	v_cmp_gt_f32_e64 s[14:15], v221, v36
	v_addc_co_u32_e64 v234, s[18:19], 0, v234, s[16:17]
	v_cmp_gt_f32_e64 s[16:17], v222, v36
	v_addc_co_u32_e64 v234, s[18:19], 0, v234, s[12:13]
	v_cmp_gt_f32_e64 s[12:13], v223, v36
	v_addc_co_u32_e64 v234, s[18:19], 0, v234, s[14:15]
	v_cmp_gt_f32_e64 s[14:15], v224, v36
	v_addc_co_u32_e64 v234, s[18:19], 0, v234, s[16:17]
	v_cmp_gt_f32_e64 s[16:17], v225, v36
	v_addc_co_u32_e64 v234, s[18:19], 0, v234, s[12:13]
	v_cmp_gt_f32_e64 s[12:13], v226, v36
	v_addc_co_u32_e64 v234, s[18:19], 0, v234, s[14:15]
	v_cmp_gt_f32_e64 s[14:15], v227, v36
	v_addc_co_u32_e64 v234, s[18:19], 0, v234, s[16:17]
	v_cmp_gt_f32_e64 s[16:17], v228, v36
	v_addc_co_u32_e64 v234, s[18:19], 0, v234, s[12:13]
	v_cmp_gt_f32_e64 s[12:13], v229, v36
	v_addc_co_u32_e64 v234, s[18:19], 0, v234, s[14:15]
	v_cmp_ge_f32_e64 s[14:15], v198, v35
	v_addc_co_u32_e64 v234, s[18:19], 0, v234, s[16:17]
; #define LAS __attribute__((address_space(3)))
; DI void attn_phase(const Params& p, const int layer, const int wid_s) {
;     ...
;       for (int i = 0; i < 8; ++i) {
;         const f32x4 r4 = *(const LAS f32x4*)(impb + 4 * i);
;         const float rv[4] = {r4[0], r4[1], r4[2], r4[3]};
; #pragma unroll
;         for (int nt = 0; nt < 8; ++nt) {
;           const float a = impv[nt]; const int ja = nt * 4 + fql;
; #pragma unroll
;           for (int c = 0; c < 4; ++c) cnt[nt] += (int)(rv[c] > a) | ((int)(rv[c] == a) & (int)((4 * i + c) < ja));
;         }
	v_cmp_ge_f32_e64 s[16:17], v199, v35
	v_addc_co_u32_e64 v234, s[18:19], 0, v234, s[12:13]
	v_cmp_ge_f32_e64 s[12:13], v200, v35
	v_addc_co_u32_e64 v235, s[18:19], 0, v235, s[14:15]
	v_cmp_ge_f32_e64 s[14:15], v201, v35
	v_addc_co_u32_e64 v235, s[18:19], 0, v235, s[16:17]
	v_cmp_ge_f32_e64 s[16:17], v202, v35
	v_addc_co_u32_e64 v235, s[18:19], 0, v235, s[12:13]
	v_cmp_ge_f32_e64 s[12:13], v203, v35
	v_addc_co_u32_e64 v235, s[18:19], 0, v235, s[14:15]
	v_cmp_ge_f32_e64 s[14:15], v204, v35
	v_addc_co_u32_e64 v235, s[18:19], 0, v235, s[16:17]
	v_cmp_ge_f32_e64 s[16:17], v205, v35
	v_addc_co_u32_e64 v235, s[18:19], 0, v235, s[12:13]
	v_cmp_ge_f32_e64 s[12:13], v206, v35
	v_addc_co_u32_e64 v235, s[18:19], 0, v235, s[14:15]
	v_cmp_ge_f32_e64 s[14:15], v207, v35
	v_addc_co_u32_e64 v235, s[18:19], 0, v235, s[16:17]
	v_cmp_ge_f32_e64 s[16:17], v208, v35
	v_addc_co_u32_e64 v235, s[18:19], 0, v235, s[12:13]
	v_cmp_ge_f32_e64 s[12:13], v209, v35
	v_addc_co_u32_e64 v235, s[18:19], 0, v235, s[14:15]
	v_cmp_ge_f32_e64 s[14:15], v210, v35
	v_addc_co_u32_e64 v235, s[18:19], 0, v235, s[16:17]
	v_cmp_ge_f32_e64 s[16:17], v211, v35
	v_addc_co_u32_e64 v235, s[18:19], 0, v235, s[12:13]
	v_cmp_ge_f32_e64 s[12:13], v212, v35
	v_addc_co_u32_e64 v235, s[18:19], 0, v235, s[14:15]
	v_cmp_ge_f32_e64 s[14:15], v213, v35
	v_addc_co_u32_e64 v235, s[18:19], 0, v235, s[16:17]
	v_cmp_ge_f32_e64 s[16:17], v214, v35
	v_addc_co_u32_e64 v235, s[18:19], 0, v235, s[12:13]
	v_cmp_ge_f32_e64 s[12:13], v215, v35
	v_addc_co_u32_e64 v235, s[18:19], 0, v235, s[14:15]
	v_cmp_ge_f32_e64 s[14:15], v216, v35
	v_addc_co_u32_e64 v235, s[18:19], 0, v235, s[16:17]
	v_cmp_ge_f32_e64 s[16:17], v217, v35
	v_addc_co_u32_e64 v235, s[18:19], 0, v235, s[12:13]
	v_cmp_gt_f32_e64 s[12:13], v218, v35
	v_cmp_ge_f32_e64 s[20:21], v218, v35
	s_and_b64 s[20:21], s[20:21], s[6:7]
	s_or_b64 s[12:13], s[12:13], s[20:21]
	v_addc_co_u32_e64 v235, s[18:19], 0, v235, s[14:15]
	v_cmp_gt_f32_e64 s[14:15], v219, v35
	v_cmp_ge_f32_e64 s[20:21], v219, v35
	s_and_b64 s[20:21], s[20:21], s[8:9]
	s_or_b64 s[14:15], s[14:15], s[20:21]
	v_addc_co_u32_e64 v235, s[18:19], 0, v235, s[16:17]
	v_cmp_gt_f32_e64 s[16:17], v220, v35
	v_cmp_ge_f32_e64 s[20:21], v220, v35
	s_and_b64 s[20:21], s[20:21], s[10:11]
	s_or_b64 s[16:17], s[16:17], s[20:21]
	v_addc_co_u32_e64 v235, s[18:19], 0, v235, s[12:13]
	v_cmp_gt_f32_e64 s[12:13], v221, v35
	v_addc_co_u32_e64 v235, s[18:19], 0, v235, s[14:15]
	v_cmp_gt_f32_e64 s[14:15], v222, v35
	v_addc_co_u32_e64 v235, s[18:19], 0, v235, s[16:17]
	v_cmp_gt_f32_e64 s[16:17], v223, v35
	v_addc_co_u32_e64 v235, s[18:19], 0, v235, s[12:13]
	v_cmp_gt_f32_e64 s[12:13], v224, v35
	v_addc_co_u32_e64 v235, s[18:19], 0, v235, s[14:15]
	v_cmp_gt_f32_e64 s[14:15], v225, v35
	v_addc_co_u32_e64 v235, s[18:19], 0, v235, s[16:17]
	v_cmp_gt_f32_e64 s[16:17], v226, v35
	v_addc_co_u32_e64 v235, s[18:19], 0, v235, s[12:13]
	v_cmp_gt_f32_e64 s[12:13], v227, v35
	v_addc_co_u32_e64 v235, s[18:19], 0, v235, s[14:15]
	v_cmp_gt_f32_e64 s[14:15], v228, v35
	v_addc_co_u32_e64 v235, s[18:19], 0, v235, s[16:17]
	v_cmp_gt_f32_e64 s[16:17], v229, v35
	v_addc_co_u32_e64 v235, s[18:19], 0, v235, s[12:13]
	v_cmp_ge_f32_e64 s[12:13], v198, v34
	v_addc_co_u32_e64 v235, s[18:19], 0, v235, s[14:15]
	v_cmp_ge_f32_e64 s[14:15], v199, v34
	v_addc_co_u32_e64 v235, s[18:19], 0, v235, s[16:17]
	v_cmp_ge_f32_e64 s[16:17], v200, v34
	v_addc_co_u32_e64 v236, s[18:19], 0, v236, s[12:13]
	v_cmp_ge_f32_e64 s[12:13], v201, v34
	v_addc_co_u32_e64 v236, s[18:19], 0, v236, s[14:15]
	v_cmp_ge_f32_e64 s[14:15], v202, v34
	v_addc_co_u32_e64 v236, s[18:19], 0, v236, s[16:17]
	v_cmp_ge_f32_e64 s[16:17], v203, v34
	v_addc_co_u32_e64 v236, s[18:19], 0, v236, s[12:13]
	v_cmp_ge_f32_e64 s[12:13], v204, v34
	v_addc_co_u32_e64 v236, s[18:19], 0, v236, s[14:15]
	v_cmp_ge_f32_e64 s[14:15], v205, v34
	v_addc_co_u32_e64 v236, s[18:19], 0, v236, s[16:17]
	v_cmp_ge_f32_e64 s[16:17], v206, v34
	v_addc_co_u32_e64 v236, s[18:19], 0, v236, s[12:13]
	v_cmp_ge_f32_e64 s[12:13], v207, v34
	v_addc_co_u32_e64 v236, s[18:19], 0, v236, s[14:15]
	v_cmp_ge_f32_e64 s[14:15], v208, v34
	v_addc_co_u32_e64 v236, s[18:19], 0, v236, s[16:17]
	v_cmp_ge_f32_e64 s[16:17], v209, v34
	v_addc_co_u32_e64 v236, s[18:19], 0, v236, s[12:13]
	v_cmp_ge_f32_e64 s[12:13], v210, v34
	v_addc_co_u32_e64 v236, s[18:19], 0, v236, s[14:15]
	v_cmp_ge_f32_e64 s[14:15], v211, v34
	v_addc_co_u32_e64 v236, s[18:19], 0, v236, s[16:17]
	v_cmp_ge_f32_e64 s[16:17], v212, v34
	v_addc_co_u32_e64 v236, s[18:19], 0, v236, s[12:13]
	v_cmp_ge_f32_e64 s[12:13], v213, v34
	v_addc_co_u32_e64 v236, s[18:19], 0, v236, s[14:15]
	v_cmp_ge_f32_e64 s[14:15], v214, v34
	v_addc_co_u32_e64 v236, s[18:19], 0, v236, s[16:17]
	v_cmp_ge_f32_e64 s[16:17], v215, v34
	v_addc_co_u32_e64 v236, s[18:19], 0, v236, s[12:13]
	v_cmp_ge_f32_e64 s[12:13], v216, v34
	v_addc_co_u32_e64 v236, s[18:19], 0, v236, s[14:15]
	v_cmp_ge_f32_e64 s[14:15], v217, v34
	v_addc_co_u32_e64 v236, s[18:19], 0, v236, s[16:17]
	v_cmp_ge_f32_e64 s[16:17], v218, v34
	v_addc_co_u32_e64 v236, s[18:19], 0, v236, s[12:13]
	v_cmp_ge_f32_e64 s[12:13], v219, v34
	v_addc_co_u32_e64 v236, s[18:19], 0, v236, s[14:15]
	v_cmp_ge_f32_e64 s[14:15], v220, v34
	v_addc_co_u32_e64 v236, s[18:19], 0, v236, s[16:17]
	v_cmp_ge_f32_e64 s[16:17], v221, v34
	v_addc_co_u32_e64 v236, s[18:19], 0, v236, s[12:13]
	v_cmp_gt_f32_e64 s[12:13], v222, v34
	v_cmp_ge_f32_e64 s[20:21], v222, v34
	s_and_b64 s[20:21], s[20:21], s[6:7]
	s_or_b64 s[12:13], s[12:13], s[20:21]
	v_addc_co_u32_e64 v236, s[18:19], 0, v236, s[14:15]
	v_cmp_gt_f32_e64 s[14:15], v223, v34
	v_cmp_ge_f32_e64 s[20:21], v223, v34
; DI int lane_get_i(int v, int srclane) { return __builtin_amdgcn_ds_bpermute(srclane << 2, v); }
; #define LAS __attribute__((address_space(3)))
; DI void attn_phase(const Params& p, const int layer, const int wid_s) {
;     ...
;       for (int i = 0; i < 8; ++i) {
;         const f32x4 r4 = *(const LAS f32x4*)(impb + 4 * i);
;         const float rv[4] = {r4[0], r4[1], r4[2], r4[3]};
; #pragma unroll
;         for (int nt = 0; nt < 8; ++nt) {
;           const float a = impv[nt]; const int ja = nt * 4 + fql;
; #pragma unroll
;           for (int c = 0; c < 4; ++c) cnt[nt] += (int)(rv[c] > a) | ((int)(rv[c] == a) & (int)((4 * i + c) < ja));
;         }
;       }
;       mk = 0;
; #pragma unroll
;       for (int nt = 0; nt < 8; ++nt) { const int ja = nt * 4 + fql; if (cnt[nt] < 8 && ja <= cur) mk |= 1u << ja; }
;       mk |= (unsigned)lane_get_i((int)mk, lane ^ 16);
;       mk |= (unsigned)lane_get_i((int)mk, lane ^ 32);
	s_and_b64 s[20:21], s[20:21], s[8:9]
	s_or_b64 s[14:15], s[14:15], s[20:21]
	v_addc_co_u32_e64 v236, s[18:19], 0, v236, s[16:17]
	v_cmp_gt_f32_e64 s[16:17], v224, v34
	v_cmp_ge_f32_e64 s[20:21], v224, v34
	s_and_b64 s[20:21], s[20:21], s[10:11]
	s_or_b64 s[16:17], s[16:17], s[20:21]
	v_addc_co_u32_e64 v236, s[18:19], 0, v236, s[12:13]
	v_cmp_gt_f32_e64 s[12:13], v225, v34
	v_addc_co_u32_e64 v236, s[18:19], 0, v236, s[14:15]
	v_cmp_gt_f32_e64 s[14:15], v226, v34
	v_addc_co_u32_e64 v236, s[18:19], 0, v236, s[16:17]
	v_cmp_gt_f32_e64 s[16:17], v227, v34
	v_addc_co_u32_e64 v236, s[18:19], 0, v236, s[12:13]
	v_cmp_gt_f32_e64 s[12:13], v228, v34
	v_addc_co_u32_e64 v236, s[18:19], 0, v236, s[14:15]
	v_cmp_gt_f32_e64 s[14:15], v229, v34
	v_addc_co_u32_e64 v236, s[18:19], 0, v236, s[16:17]
	v_cmp_ge_f32_e64 s[16:17], v198, v33
	v_addc_co_u32_e64 v236, s[18:19], 0, v236, s[12:13]
	v_cmp_ge_f32_e64 s[12:13], v199, v33
	v_addc_co_u32_e64 v236, s[18:19], 0, v236, s[14:15]
	v_cmp_ge_f32_e64 s[14:15], v200, v33
	v_addc_co_u32_e64 v237, s[18:19], 0, v237, s[16:17]
	v_cmp_ge_f32_e64 s[16:17], v201, v33
	v_addc_co_u32_e64 v237, s[18:19], 0, v237, s[12:13]
	v_cmp_ge_f32_e64 s[12:13], v202, v33
	v_addc_co_u32_e64 v237, s[18:19], 0, v237, s[14:15]
	v_cmp_ge_f32_e64 s[14:15], v203, v33
	v_addc_co_u32_e64 v237, s[18:19], 0, v237, s[16:17]
	v_cmp_ge_f32_e64 s[16:17], v204, v33
	v_addc_co_u32_e64 v237, s[18:19], 0, v237, s[12:13]
	v_cmp_ge_f32_e64 s[12:13], v205, v33
	v_addc_co_u32_e64 v237, s[18:19], 0, v237, s[14:15]
	v_cmp_ge_f32_e64 s[14:15], v206, v33
	v_addc_co_u32_e64 v237, s[18:19], 0, v237, s[16:17]
	v_cmp_ge_f32_e64 s[16:17], v207, v33
	v_addc_co_u32_e64 v237, s[18:19], 0, v237, s[12:13]
	v_cmp_ge_f32_e64 s[12:13], v208, v33
	v_addc_co_u32_e64 v237, s[18:19], 0, v237, s[14:15]
	v_cmp_ge_f32_e64 s[14:15], v209, v33
	v_addc_co_u32_e64 v237, s[18:19], 0, v237, s[16:17]
	v_cmp_ge_f32_e64 s[16:17], v210, v33
	v_addc_co_u32_e64 v237, s[18:19], 0, v237, s[12:13]
	v_cmp_ge_f32_e64 s[12:13], v211, v33
	v_addc_co_u32_e64 v237, s[18:19], 0, v237, s[14:15]
	v_cmp_ge_f32_e64 s[14:15], v212, v33
	v_addc_co_u32_e64 v237, s[18:19], 0, v237, s[16:17]
	v_cmp_ge_f32_e64 s[16:17], v213, v33
	v_addc_co_u32_e64 v237, s[18:19], 0, v237, s[12:13]
	v_cmp_ge_f32_e64 s[12:13], v214, v33
	v_addc_co_u32_e64 v237, s[18:19], 0, v237, s[14:15]
	v_cmp_ge_f32_e64 s[14:15], v215, v33
	v_addc_co_u32_e64 v237, s[18:19], 0, v237, s[16:17]
	v_cmp_ge_f32_e64 s[16:17], v216, v33
	v_addc_co_u32_e64 v237, s[18:19], 0, v237, s[12:13]
	v_cmp_ge_f32_e64 s[12:13], v217, v33
	v_addc_co_u32_e64 v237, s[18:19], 0, v237, s[14:15]
	v_cmp_ge_f32_e64 s[14:15], v218, v33
	v_addc_co_u32_e64 v237, s[18:19], 0, v237, s[16:17]
	v_cmp_ge_f32_e64 s[16:17], v219, v33
	v_addc_co_u32_e64 v237, s[18:19], 0, v237, s[12:13]
	v_cmp_ge_f32_e64 s[12:13], v220, v33
	v_addc_co_u32_e64 v237, s[18:19], 0, v237, s[14:15]
	v_cmp_ge_f32_e64 s[14:15], v221, v33
	v_addc_co_u32_e64 v237, s[18:19], 0, v237, s[16:17]
	v_cmp_ge_f32_e64 s[16:17], v222, v33
	v_addc_co_u32_e64 v237, s[18:19], 0, v237, s[12:13]
	v_cmp_ge_f32_e64 s[12:13], v223, v33
	v_addc_co_u32_e64 v237, s[18:19], 0, v237, s[14:15]
	v_cmp_ge_f32_e64 s[14:15], v224, v33
	v_addc_co_u32_e64 v237, s[18:19], 0, v237, s[16:17]
	v_cmp_ge_f32_e64 s[16:17], v225, v33
	v_addc_co_u32_e64 v237, s[18:19], 0, v237, s[12:13]
	v_cmp_gt_f32_e64 s[12:13], v226, v33
	v_cmp_ge_f32_e64 s[20:21], v226, v33
	s_and_b64 s[20:21], s[20:21], s[6:7]
	s_or_b64 s[12:13], s[12:13], s[20:21]
	v_addc_co_u32_e64 v237, s[18:19], 0, v237, s[14:15]
	v_cmp_gt_f32_e64 s[14:15], v227, v33
	v_cmp_ge_f32_e64 s[20:21], v227, v33
	s_and_b64 s[20:21], s[20:21], s[8:9]
	s_or_b64 s[14:15], s[14:15], s[20:21]
	v_addc_co_u32_e64 v237, s[18:19], 0, v237, s[16:17]
	v_cmp_gt_f32_e64 s[16:17], v228, v33
	v_cmp_ge_f32_e64 s[20:21], v228, v33
	s_and_b64 s[20:21], s[20:21], s[10:11]
	s_or_b64 s[16:17], s[16:17], s[20:21]
	v_addc_co_u32_e64 v237, s[18:19], 0, v237, s[12:13]
	v_cmp_gt_f32_e64 s[12:13], v229, v33
	v_addc_co_u32_e64 v237, s[18:19], 0, v237, s[14:15]
	s_nop 1
	v_addc_co_u32_e64 v237, s[18:19], 0, v237, s[16:17]
	v_addc_co_u32_e64 v237, s[18:19], 0, v237, s[12:13]
	v_add_u32_e32 v238, 0, v123
	v_add_u32_e32 v239, 4, v123
	v_add_u32_e32 v240, 8, v123
	v_add_u32_e32 v241, 12, v123
	v_add_u32_e32 v242, 16, v123
	v_add_u32_e32 v243, 20, v123
	v_add_u32_e32 v244, 24, v123
	v_add_u32_e32 v245, 28, v123
	v_cmp_gt_u32_e64 s[12:13], 8, v230
	v_cmp_ge_i32_e64 s[14:15], s54, v238
	v_lshlrev_b32_e64 v238, v238, 1
	s_and_b64 s[12:13], s[12:13], s[14:15]
	s_nop 1
	v_cndmask_b32_e64 v238, 0, v238, s[12:13]
	v_cmp_gt_u32_e64 s[16:17], 8, v231
	v_cmp_ge_i32_e64 s[20:21], s54, v239
	v_lshlrev_b32_e64 v239, v239, 1
	s_and_b64 s[16:17], s[16:17], s[20:21]
	s_nop 1
	v_cndmask_b32_e64 v239, 0, v239, s[16:17]
	v_cmp_gt_u32_e64 s[12:13], 8, v232
	v_cmp_ge_i32_e64 s[14:15], s54, v240
	v_lshlrev_b32_e64 v240, v240, 1
	s_and_b64 s[12:13], s[12:13], s[14:15]
	s_nop 1
	v_cndmask_b32_e64 v240, 0, v240, s[12:13]
	v_cmp_gt_u32_e64 s[16:17], 8, v233
	v_cmp_ge_i32_e64 s[20:21], s54, v241
	v_lshlrev_b32_e64 v241, v241, 1
	s_and_b64 s[16:17], s[16:17], s[20:21]
	s_nop 1
	v_cndmask_b32_e64 v241, 0, v241, s[16:17]
	v_cmp_gt_u32_e64 s[12:13], 8, v234
	v_cmp_ge_i32_e64 s[14:15], s54, v242
	v_lshlrev_b32_e64 v242, v242, 1
	s_and_b64 s[12:13], s[12:13], s[14:15]
	s_nop 1
	v_cndmask_b32_e64 v242, 0, v242, s[12:13]
	v_cmp_gt_u32_e64 s[16:17], 8, v235
	v_cmp_ge_i32_e64 s[20:21], s54, v243
	v_lshlrev_b32_e64 v243, v243, 1
	s_and_b64 s[16:17], s[16:17], s[20:21]
	s_nop 1
	v_cndmask_b32_e64 v243, 0, v243, s[16:17]
	v_cmp_gt_u32_e64 s[12:13], 8, v236
	v_cmp_ge_i32_e64 s[14:15], s54, v244
	v_lshlrev_b32_e64 v244, v244, 1
	s_and_b64 s[12:13], s[12:13], s[14:15]
	s_nop 1
	v_cndmask_b32_e64 v244, 0, v244, s[12:13]
	v_cmp_gt_u32_e64 s[16:17], 8, v237
	v_cmp_ge_i32_e64 s[20:21], s54, v245
	v_lshlrev_b32_e64 v245, v245, 1
	s_and_b64 s[16:17], s[16:17], s[20:21]
	s_nop 1
	v_cndmask_b32_e64 v245, 0, v245, s[16:17]
	v_or3_b32 v0, v238, v239, v240
	v_or3_b32 v2, v241, v242, v243
	v_or3_b32 v0, v0, v244, v245
	v_or_b32_e32 v0, v0, v2
	ds_bpermute_b32 v2, v179, v0
	s_waitcnt lgkmcnt(0)
; DI int lane_get_i(int v, int srclane) { return __builtin_amdgcn_ds_bpermute(srclane << 2, v); }
; DI void attn_phase(const Params& p, const int layer, const int wid_s) {
;     ...
;       mk |= (unsigned)lane_get_i((int)mk, lane ^ 16);
;       mk |= (unsigned)lane_get_i((int)mk, lane ^ 32);
;       }
;       selmask = mk;
	v_or_b32_e32 v0, v0, v2
	ds_bpermute_b32 v2, v180, v0
	v_readlane_b32 s84, v252, 44
	v_readlane_b32 s86, v252, 46
	v_readlane_b32 s87, v252, 47
	v_readlane_b32 s88, v252, 48
	v_readlane_b32 s89, v252, 49
	v_readlane_b32 s90, v252, 50
	v_readlane_b32 s91, v252, 51
	v_readlane_b32 s92, v252, 52
	v_readlane_b32 s93, v252, 53
	v_readlane_b32 s94, v252, 54
	v_readlane_b32 s95, v252, 55
	v_readlane_b32 s96, v252, 56
	v_readlane_b32 s97, v252, 57
	v_readlane_b32 s98, v252, 58
	v_readlane_b32 s99, v252, 59
	v_readlane_b32 s56, v250, 21
	v_readlane_b32 s58, v250, 23
	v_readlane_b32 s62, v249, 55
	v_readlane_b32 s78, v250, 34
	v_readlane_b32 s80, v250, 36
	v_readlane_b32 s85, v252, 45
	v_readlane_b32 s98, v249, 51
	v_readlane_b32 s96, v249, 49
	v_readlane_b32 s94, v249, 47
	v_readlane_b32 s92, v249, 45
	v_readlane_b32 s86, v249, 43
	v_readlane_b32 s57, v250, 22
	v_readlane_b32 s59, v250, 24
	v_readlane_b32 s88, v250, 29
	s_mov_b32 s77, s39
	v_readlane_b32 s39, v248, 2
	v_readlane_b32 s76, v250, 38
	v_readlane_b32 s63, v249, 56
	v_readlane_b32 s79, v250, 35
	v_readlane_b32 s81, v250, 37
	s_movk_i32 s83, 0x2000
	s_mov_b32 s82, 0x800000
	s_movk_i32 s85, 0x4000
	s_mov_b32 s84, 0x14000
	v_readlane_b32 s99, v249, 52
	v_readlane_b32 s97, v249, 50
	v_readlane_b32 s95, v249, 48
	v_readlane_b32 s93, v249, 46
	v_readlane_b32 s87, v249, 44
	v_readlane_b32 s64, v249, 57
	s_mov_b32 s57, 0xffff
	v_readlane_b32 s55, v250, 33
	s_movk_i32 s59, 0x1000
	v_readlane_b32 s61, v249, 54
	v_readlane_b32 s60, v249, 53
	v_readlane_b32 s89, v250, 30
	v_readlane_b32 s90, v250, 31
	v_readlane_b32 s91, v250, 32
	s_waitcnt lgkmcnt(0)
	v_or_b32_e32 v5, v0, v2
